# code after the first grid barrier shifted by 16 bytes (instruction-fetch alignment trial)
# speedup vs baseline: 1.0051x; 1.0051x over previous
; #define PG8_STAGE(bufoff, gbase, voff) do { _Pragma("unroll") for (int _i = 0; _i < 2; ++_i) \
;         __builtin_amdgcn_global_load_lds((const unsigned*)((const char*)(gbase) + (voff)[_i]), (PG8_LAS unsigned*)(lds + (bufoff) + ldsw + _i * 8192), 16, 0, 0); } while (0)
; #define PG8_BAR __builtin_amdgcn_s_barrier()
; template <class Epi, class Sched, bool ALIGN_EPI = false, bool SP2 = false>
; __device__ __forceinline__ void gemm_phase(PG8_LAS unsigned char* lds, const Gemm g, const Sched& S, const Epi& E) {
;     ...
;     const int wid = __builtin_amdgcn_readfirstlane(tid >> 6), lane = tid & 63, wr = wid >> 2, wc = wid & 3, fr = lane & 15, fq = lane >> 4;
;     const int K = g.K, nt = K / BK;
;     unsigned voffA[2], voffB[2];
; #pragma unroll
;     for (int i = 0; i < 2; ++i) { int R, C; stage_rc(tid * 16 + i * 8192, R, C); const int Rb = Epi::PERM ? ((R & ~31) + perm32(R & 31)) : R;
;         voffA[i] = (unsigned)(R * K + C) * 2u; voffB[i] = (unsigned)(Rb * K + C) * 2u; }
;     const size_t kstep = (size_t)(BK * 2);
;     const size_t hstep = (size_t)HALF * K * 2;
;     const size_t tstep = 2 * hstep;
;     const unsigned ldsw = (unsigned)wid * 1024u;
;     const int aoff = lds_byte(wr * 64 + fr, fq * 8), boff = lds_byte(wc * 32 + fr, fq * 8);
;     ...
;     Unit cur, nxt; int ui = 0;
;     if (!S.next(0, cur)) return;
;     f32x4 acc[2][2][4][2];
; #pragma unroll
;     for (int a = 0; a < 2; ++a)
; #pragma unroll
;         for (int b = 0; b < 2; ++b)
; #pragma unroll
;             for (int m = 0; m < 4; ++m)
; #pragma unroll
;                 for (int n = 0; n < 2; ++n) acc[a][b][m][n] = (f32x4){0.f, 0.f, 0.f, 0.f};
;     bf16x8 At[4][2], B0[2][2], B1[2][2];
;     const char* cA = (const char*)g.A + (size_t)cur.pm * tstep; const char* cB = (const char*)g.Bt + (size_t)cur.pn * tstep;
;     S.a_ready(cur);
;     if constexpr (SP2) {
;         PG8_STAGE(PG8_SB(0, 0), cB, voffB); PG8_STAGE(PG8_SB(0, 1), cB + hstep, voffB); PG8_STAGE(PG8_SA(0, 0), cA, voffA); PG8_STAGE(PG8_SA(0, 1), cA + hstep, voffA);
;         if (wr == 1) PG8_BAR;
.LBB0_183:
	s_nop 0
	s_nop 0
	s_nop 0
	s_nop 0
	s_or_b64 exec, exec, s[0:1]
	v_readlane_b32 s4, v235, 8
	v_readlane_b32 s5, v235, 9
	v_and_b32_e32 v0, 7, v189
	v_lshlrev_b32_e32 v0, 3, v0
	v_add_u32_e32 v0, 0x3800, v0
	s_nop 1
	global_load_dwordx2 v[0:1], v0, s[4:5] sc1
	s_waitcnt vmcnt(0)
	v_add_u32_e32 v0, v0, v1
	v_cmp_ne_u32_e32 vcc, 17, v0
	s_cmp_lg_u64 vcc, 0
	s_cselect_b32 s4, 1, 0
	v_mov_b32_e32 v0, 0x20170
	v_mov_b32_e32 v1, s4
	ds_write_b32 v0, v1
	v_readlane_b32 s0, v235, 2
	v_readlane_b32 s2, v235, 4
	v_readlane_b32 s1, v235, 3
	v_readlane_b32 s3, v235, 5
	s_add_u32 s0, s2, 0x7000000
	s_addc_u32 s1, s3, 0
	v_writelane_b32 v235, s0, 33
	v_mov_b32_e32 v9, v189
	s_waitcnt lgkmcnt(0)
	v_writelane_b32 v235, s1, 34
	s_barrier
	v_readlane_b32 s0, v235, 0
	s_cmpk_lt_i32 s0, 0xb00
	s_cselect_b64 s[2:3], -1, 0
	v_writelane_b32 v235, s2, 35
	s_cmpk_gt_i32 s0, 0xaff
	v_readfirstlane_b32 s1, v9
	v_writelane_b32 v235, s3, 36
	s_cbranch_scc1 .LBB0_199
	v_lshlrev_b32_e32 v0, 4, v9
	v_add_u32_e32 v1, 0x2000, v0
	v_ashrrev_i32_e32 v2, 31, v1
	v_lshrrev_b32_e32 v2, 22, v2
	v_add_u32_e32 v2, v1, v2
	v_ashrrev_i32_e32 v8, 10, v2
	v_mul_i32_i24_e32 v2, 0x400, v8
	v_sub_u32_e32 v1, v1, v2
	v_lshrrev_b32_e32 v2, 4, v1
	v_bitop3_b32 v1, v2, v1, 32 bitop3:0x6c
	v_ashrrev_i32_e32 v2, 31, v1
	v_lshrrev_b32_e32 v2, 26, v2
	v_add_u32_e32 v2, v1, v2
	v_lshlrev_b32_e32 v3, 3, v8
	v_ashrrev_i32_e32 v10, 6, v2
	v_and_b32_e32 v3, -16, v3
	v_add_u32_e32 v3, v10, v3
	v_and_b32_e32 v4, 3, v10
	s_mov_b32 s0, 0x1fffe0
	v_lshrrev_b32_e32 v5, 2, v3
	v_lshlrev_b32_e32 v6, 1, v3
	v_and_b32_e32 v2, 0xc0, v2
	v_and_or_b32 v4, v3, s0, v4
	v_and_b32_e32 v5, 4, v5
	v_and_b32_e32 v6, 24, v6
	v_sub_u32_e32 v1, v1, v2
	v_mov_b32_e32 v2, 1
	v_or3_b32 v4, v4, v5, v6
	v_lshlrev_b32_e32 v5, 5, v8
	v_ashrrev_i16_sdwa v1, v2, sext(v1) dst_sel:DWORD dst_unused:UNUSED_PAD src0_sel:DWORD src1_sel:BYTE_0
	v_and_b32_e32 v5, 32, v5
	v_bfe_i32 v11, v1, 0, 16
	v_add_lshl_u32 v1, v5, v11, 1
	v_lshl_add_u32 v128, v4, 11, v1
	v_lshl_add_u32 v130, v3, 11, v1
	v_bfe_i32 v1, v9, 27, 1
	v_lshrrev_b32_e32 v1, 22, v1
	v_add_u32_e32 v1, v0, v1
	v_and_b32_e32 v1, 0xfffffc00, v1
	v_sub_u32_e32 v0, v0, v1
	v_lshrrev_b32_e32 v1, 4, v0
	v_ashrrev_i32_e32 v3, 31, v9
	v_bitop3_b32 v0, v1, v0, 32 bitop3:0x6c
	v_lshrrev_b32_e32 v3, 26, v3
	v_ashrrev_i32_e32 v1, 31, v0
	v_add_u32_e32 v3, v9, v3
	v_readlane_b32 s4, v235, 2
	v_lshrrev_b32_e32 v1, 26, v1
	v_ashrrev_i32_e32 v13, 6, v3
	v_readlane_b32 s6, v235, 4
	v_add_u32_e32 v1, v0, v1
	v_lshlrev_b32_e32 v3, 3, v13
	v_readlane_b32 s7, v235, 5
	s_add_u32 s33, s6, 0x200000
	v_ashrrev_i32_e32 v12, 6, v1
	v_and_b32_e32 v3, -16, v3
	v_readlane_b32 s3, v235, 0
	s_addc_u32 s34, s7, 0
	v_add_u32_e32 v3, v12, v3
	v_and_b32_e32 v4, 3, v12
	s_ashr_i32 s36, s3, 31
	v_and_or_b32 v4, v3, s0, v4
	s_lshr_b32 s0, s36, 29
	s_add_i32 s0, s3, s0
	s_ashr_i32 s4, s1, 6
	s_ashr_i32 s2, s0, 3
	s_and_b32 s0, s0, -8
	s_ashr_i32 s6, s1, 8
	s_lshl_b32 s35, s4, 10
	s_sub_i32 s0, s3, s0
	s_cmp_lt_i32 s0, 0
	s_movk_i32 s37, 0x161
	s_cselect_b32 s3, s37, 0x160
	s_mul_i32 s0, s0, s3
	s_add_i32 s0, s0, s2
	s_mul_hi_i32 s2, s0, 0x2e8ba2e9
	s_lshr_b32 s3, s2, 31
	s_ashr_i32 s2, s2, 4
	s_add_i32 s2, s2, s3
	s_lshl_b32 s3, s2, 2
	s_mulk_i32 s2, 0x58
	s_sub_i32 s2, s0, s2
	s_bfe_i32 s0, s2, 0x80000
	v_readlane_b32 s5, v235, 3
	s_bfe_u32 s0, s0, 0x2000d
	s_add_i32 s5, s2, s0
	s_bfe_i32 s0, s5, 0x80000
	s_and_b32 s5, s5, 0xfc
	s_sub_i32 s2, s2, s5
	s_sext_i32_i16 s0, s0
	s_sext_i32_i8 s2, s2
	v_lshrrev_b32_e32 v5, 2, v3
	v_lshlrev_b32_e32 v6, 1, v3
	v_and_b32_e32 v1, 0xc0, v1
	s_lshr_b32 s0, s0, 2
	s_add_i32 s20, s3, s2
	v_and_b32_e32 v5, 4, v5
	v_and_b32_e32 v6, 24, v6
	v_sub_u32_e32 v0, v0, v1
	s_ashr_i32 s21, s20, 31
	s_bfe_i64 s[8:9], s[0:1], 0x100000
	v_or3_b32 v4, v4, v5, v6
	v_lshlrev_b32_e32 v5, 5, v13
	v_ashrrev_i16_sdwa v0, v2, sext(v0) dst_sel:DWORD dst_unused:UNUSED_PAD src0_sel:DWORD src1_sel:BYTE_0
	s_lshl_b64 s[2:3], s[20:21], 19
	s_lshl_b64 s[8:9], s[8:9], 19
	v_and_b32_e32 v5, 32, v5
	v_bfe_i32 v14, v0, 0, 16
	s_add_u32 s24, s33, s8
	v_add_lshl_u32 v0, v5, v14, 1
	s_addc_u32 s25, s34, s9
	s_add_i32 s21, s35, 0
	v_lshl_add_u32 v132, v4, 11, v0
	s_add_i32 m0, s21, 0x10000
	v_lshl_add_u32 v134, v3, 11, v0
	global_load_lds_dwordx4 v132, s[24:25]
	s_add_i32 m0, s21, 0x12000
	s_add_u32 s8, s24, 0x40000
	global_load_lds_dwordx4 v128, s[24:25]
	s_addc_u32 s9, s25, 0
	s_add_i32 m0, s21, 0x14000
	v_mov_b32_e32 v133, 0
	global_load_lds_dwordx4 v132, s[8:9]
	s_add_i32 m0, s21, 0x16000
	v_mov_b32_e32 v129, v133
	global_load_lds_dwordx4 v128, s[8:9]
	v_readlane_b32 s8, v235, 31
	v_readlane_b32 s9, v235, 32
	s_add_u32 s22, s8, s2
	s_addc_u32 s23, s9, s3
	s_add_i32 s38, s21, 0x2000
	s_mov_b32 m0, s21
	s_add_u32 s2, s22, 0x40000
	global_load_lds_dwordx4 v134, s[22:23]
	s_mov_b32 m0, s38
	s_addc_u32 s3, s23, 0
	s_add_i32 s39, s21, 0x4000
	global_load_lds_dwordx4 v130, s[22:23]
	s_mov_b32 m0, s39
	s_add_i32 s40, s21, 0x6000
	global_load_lds_dwordx4 v134, s[2:3]
	s_mov_b32 m0, s40
	v_mov_b32_e32 v135, v133
	global_load_lds_dwordx4 v130, s[2:3]
	v_mov_b32_e32 v131, v133
	s_cmp_eq_u32 s6, 1
	s_mov_b32 s41, 0
	v_lshl_add_u64 v[6:7], s[24:25], 0, v[132:133]
	v_lshl_add_u64 v[4:5], s[24:25], 0, v[128:129]
	v_lshl_add_u64 v[0:1], s[22:23], 0, v[134:135]
	s_cselect_b64 s[2:3], -1, 0
	s_cmp_lg_u32 s6, 1
	v_lshl_add_u64 v[2:3], s[22:23], 0, v[130:131]
	s_cbranch_scc1 .LBB0_186
	s_barrier
